# phase0: also software-pipelined the modulation GEMV loop (one 4-k iteration of loads in flight, clamped last prefetch); bit-identical
# baseline (speedup 1.0000x reference)
.LBB0_1145:
	s_or_b64 exec, exec, s[0:1]
	s_add_i32 s0, s46, 0xff80
	s_and_b32 s1, s0, 0xffff
	s_mul_i32 s1, s1, 0xaaab
	s_lshr_b32 s8, s1, 22
	s_mul_i32 s1, s8, 0x60
	v_ashrrev_i32_e32 v3, 6, v14
	s_sub_i32 s0, s0, s1
	v_lshlrev_b32_e32 v4, 7, v3
	v_readlane_b32 s64, v254, 1
	s_lshl_b32 s0, s0, 6
	s_lshl_b32 s2, s8, 10
	v_ashrrev_i32_e32 v5, 31, v4
	v_readlane_b32 s72, v254, 9
	v_readlane_b32 s73, v254, 10
	s_and_b32 s0, s0, 0xffc0
	v_and_b32_e32 v15, 63, v14
	v_lshl_add_u64 v[4:5], s[2:3], 0, v[4:5]
	v_mov_b64_e32 v[6:7], s[72:73]
	v_or_b32_e32 v2, s0, v15
	v_mad_u64_u32 v[6:7], s[0:1], v4, s57, v[6:7]
	v_mad_i32_i24 v7, v5, s57, v7
	v_lshlrev_b32_e32 v0, 2, v2
	v_lshl_add_u64 v[4:5], v[6:7], 0, v[0:1]
	v_mov_b32_e32 v6, 0
	v_lshl_add_u32 v0, v3, 9, 0
	s_mov_b64 s[0:1], 0
	v_mov_b32_e32 v7, v6
	v_mov_b32_e32 v8, v6
	v_mov_b32_e32 v9, v6
	v_mov_b32_e32 v10, v6
	v_mov_b32_e32 v11, v6
	v_mov_b32_e32 v12, v6
	v_mov_b32_e32 v13, v6
	v_mov_b32_e32 v16, v6
	s_waitcnt vmcnt(0) lgkmcnt(0)
	s_barrier
	v_readlane_b32 s65, v254, 2
	v_readlane_b32 s66, v254, 3
	v_readlane_b32 s67, v254, 4
	v_readlane_b32 s68, v254, 5
	v_readlane_b32 s69, v254, 6
	v_readlane_b32 s70, v254, 7
	v_readlane_b32 s71, v254, 8
	v_readlane_b32 s74, v254, 11
	v_readlane_b32 s75, v254, 12
	v_readlane_b32 s76, v254, 13
	v_readlane_b32 s77, v254, 14
	v_readlane_b32 s78, v254, 15
	v_readlane_b32 s79, v254, 16
	v_add_co_u32_e32 v20, vcc, s57, v4
	global_load_dword v76, v[4:5], off
	s_nop 0
	v_addc_co_u32_e32 v21, vcc, 0, v5, vcc
	v_add_co_u32_e32 v22, vcc, s48, v4
	s_nop 1
	v_addc_co_u32_e32 v23, vcc, 0, v5, vcc
	v_add_co_u32_e32 v18, vcc, 0x12000, v4
	s_nop 1
	v_addc_co_u32_e32 v19, vcc, 0, v5, vcc
	global_load_dword v77, v[20:21], off
	global_load_dword v78, v[22:23], off
	global_load_dword v79, v[18:19], off
.LBB0_1146:
	s_add_u32 s0, s0, 0x18000
	s_addc_u32 s1, s1, 0
	s_min_u32 s9, s0, 0x2e8000
	v_add_co_u32_e32 v18, vcc, s9, v4
	s_nop 1
	v_addc_co_u32_e32 v19, vcc, 0, v5, vcc
	v_add_co_u32_e32 v20, vcc, s57, v18
	s_nop 1
	v_addc_co_u32_e32 v21, vcc, 0, v19, vcc
	v_add_co_u32_e32 v22, vcc, s48, v18
	s_nop 1
	v_addc_co_u32_e32 v23, vcc, 0, v19, vcc
	v_add_co_u32_e32 v80, vcc, 0x12000, v18
	s_nop 1
	v_addc_co_u32_e32 v81, vcc, 0, v19, vcc
	s_waitcnt vmcnt(0)
	v_mov_b32_e32 v54, v76
	v_mov_b32_e32 v56, v77
	v_mov_b32_e32 v58, v78
	v_mov_b32_e32 v60, v79
	global_load_dword v76, v[18:19], off
	global_load_dword v77, v[20:21], off
	global_load_dword v78, v[22:23], off
	global_load_dword v79, v[80:81], off
	ds_read_b128 v[18:21], v0 offset:4096
	ds_read_b128 v[22:25], v0 offset:8192
	ds_read_b128 v[26:29], v0 offset:12288
	ds_read_b128 v[30:33], v0 offset:16384
	ds_read_b128 v[34:37], v0 offset:20480
	ds_read_b128 v[38:41], v0 offset:24576
	ds_read_b128 v[42:45], v0 offset:28672
	ds_read_b128 v[46:49], v0
	ds_read_b128 v[50:53], v0 offset:32768
	s_waitcnt lgkmcnt(8)
	v_mov_b32_e32 v63, v18
	s_waitcnt lgkmcnt(7)
	v_mov_b32_e32 v64, v22
	s_waitcnt lgkmcnt(6)
	v_mov_b32_e32 v65, v26
	s_waitcnt lgkmcnt(1)
	v_mov_b32_e32 v62, v46
	v_mov_b32_e32 v66, v30
	v_mov_b32_e32 v67, v34
	v_mov_b32_e32 v68, v38
	v_mov_b32_e32 v69, v42
	v_mov_b32_e32 v18, v47
	v_mov_b32_e32 v26, v23
	v_mov_b32_e32 v34, v31
	v_mov_b32_e32 v42, v39
	v_mov_b32_e32 v22, v48
	v_mov_b32_e32 v23, v20
	v_mov_b32_e32 v30, v24
	v_mov_b32_e32 v31, v28
	v_mov_b32_e32 v38, v32
	v_mov_b32_e32 v39, v36
	v_mov_b32_e32 v46, v40
	v_mov_b32_e32 v47, v44
	v_mov_b32_e32 v20, v49
	v_mov_b32_e32 v28, v25
	v_mov_b32_e32 v36, v33
	v_mov_b32_e32 v44, v41
	v_add_u32_e32 v0, 16, v0
	s_cmp_eq_u32 s0, 0x300000
	v_pk_fma_f32 v[6:7], v[54:55], v[62:63], v[6:7] op_sel_hi:[0,1,1]
	v_pk_fma_f32 v[8:9], v[54:55], v[64:65], v[8:9] op_sel_hi:[0,1,1]
	v_pk_fma_f32 v[10:11], v[54:55], v[66:67], v[10:11] op_sel_hi:[0,1,1]
	v_pk_fma_f32 v[12:13], v[54:55], v[68:69], v[12:13] op_sel_hi:[0,1,1]
	s_waitcnt lgkmcnt(0)
	v_fmac_f32_e32 v16, v54, v50
	v_pk_fma_f32 v[6:7], v[56:57], v[18:19], v[6:7] op_sel_hi:[0,1,1]
	v_pk_fma_f32 v[8:9], v[56:57], v[26:27], v[8:9] op_sel_hi:[0,1,1]
	v_pk_fma_f32 v[10:11], v[56:57], v[34:35], v[10:11] op_sel_hi:[0,1,1]
	v_pk_fma_f32 v[12:13], v[56:57], v[42:43], v[12:13] op_sel_hi:[0,1,1]
	v_fmac_f32_e32 v16, v56, v51
	v_pk_fma_f32 v[6:7], v[58:59], v[22:23], v[6:7] op_sel_hi:[0,1,1]
	v_pk_fma_f32 v[8:9], v[58:59], v[30:31], v[8:9] op_sel_hi:[0,1,1]
	v_pk_fma_f32 v[10:11], v[58:59], v[38:39], v[10:11] op_sel_hi:[0,1,1]
	v_pk_fma_f32 v[12:13], v[58:59], v[46:47], v[12:13] op_sel_hi:[0,1,1]
	v_fmac_f32_e32 v16, v58, v52
	v_pk_fma_f32 v[6:7], v[60:61], v[20:21], v[6:7] op_sel_hi:[0,1,1]
	v_pk_fma_f32 v[8:9], v[60:61], v[28:29], v[8:9] op_sel_hi:[0,1,1]
	v_pk_fma_f32 v[10:11], v[60:61], v[36:37], v[10:11] op_sel_hi:[0,1,1]
	v_pk_fma_f32 v[12:13], v[60:61], v[44:45], v[12:13] op_sel_hi:[0,1,1]
	v_fmac_f32_e32 v16, v60, v53
	s_cbranch_scc0 .LBB0_1146
	v_lshl_add_u32 v4, v15, 2, 0
	s_movk_i32 s0, 0x900
	v_mad_u64_u32 v[18:19], s[0:1], v3, s0, v[4:5]
	s_movk_i32 s0, 0x240
	s_nop 0
	v_cmp_gt_i32_e32 vcc, s0, v14
	ds_write2st64_b32 v18, v6, v7 offset0:144 offset1:145
	ds_write2st64_b32 v18, v8, v9 offset0:146 offset1:147
	ds_write2st64_b32 v18, v10, v11 offset0:148 offset1:149
	ds_write2st64_b32 v18, v12, v13 offset0:150 offset1:151
	ds_write_b32 v18, v16 offset:38912
	s_waitcnt lgkmcnt(0)
	s_barrier
	s_and_saveexec_b64 s[0:1], vcc
	s_cbranch_execz .LBB0_1150
	s_mul_i32 s9, s8, 0x1800
	s_and_b32 s9, s9, 0xf800
	v_readlane_b32 s64, v254, 1
	v_add_lshl_u32 v0, v2, s9, 2
	v_readlane_b32 s74, v254, 11
	v_readlane_b32 s75, v254, 12
	s_mul_i32 s10, s8, 9
	s_mov_b64 s[8:9], 0
	v_lshl_add_u64 v[6:7], s[74:75], 0, v[0:1]
	v_lshlrev_b32_e32 v0, 2, v2
	v_lshl_add_u64 v[2:3], s[52:53], 0, v[0:1]
	v_readlane_b32 s65, v254, 2
	v_readlane_b32 s66, v254, 3
	v_readlane_b32 s67, v254, 4
	v_readlane_b32 s68, v254, 5
	v_readlane_b32 s69, v254, 6
	v_readlane_b32 s70, v254, 7
	v_readlane_b32 s71, v254, 8
	v_readlane_b32 s72, v254, 9
	v_readlane_b32 s73, v254, 10
	v_readlane_b32 s76, v254, 13
	v_readlane_b32 s77, v254, 14
	v_readlane_b32 s78, v254, 15
	v_readlane_b32 s79, v254, 16
